# y_b pair-major layout (full-line A loads in out-proj) plus attention tile loop: LDS waits recomputed per consumer (counted lgkmcnt instead of full waits before each P*V MFMA group), instruction order
# speedup vs baseline: 1.1741x; 1.0068x over previous
.LBB0_423:
	s_lshl_b32 s16, s19, 14
	s_add_i32 s4, s16, 16
	v_add_u32_e32 v96, s4, v185
	ds_read_b128 v[198:201], v96 offset:49152
	ds_read_b128 v[202:205], v96 offset:57344
	v_xor_b32_e32 v80, 0x80000000, v195
	v_mov_b32_e32 v81, v80
	v_mov_b64_e32 v[82:83], v[80:81]
	v_mov_b64_e32 v[84:85], v[80:81]
	v_mov_b64_e32 v[86:87], v[80:81]
	v_mov_b64_e32 v[88:89], v[80:81]
	v_mov_b64_e32 v[90:91], v[80:81]
	v_mov_b64_e32 v[92:93], v[80:81]
	v_mov_b64_e32 v[94:95], v[80:81]
	v_exp_f32_e32 v221, v64
	v_add_f32_e32 v64, 0, v152
	s_waitcnt lgkmcnt(1)
	v_mfma_f32_32x32x16_bf16 v[96:111], v[198:201], v[124:127], v[80:95]
	v_add_f32_e32 v64, v153, v64
	v_add_f32_e32 v64, v154, v64
	v_add_u32_e32 v197, s4, v189
	v_add_f32_e32 v64, v155, v64
	v_add_f32_e32 v64, v156, v64
	v_add_f32_e32 v64, v157, v64
	v_add_f32_e32 v64, v158, v64
	s_waitcnt lgkmcnt(0)
	v_mfma_f32_32x32x16_bf16 v[80:95], v[202:205], v[124:127], v[80:95]
	ds_read_b128 v[198:201], v197 offset:49152
	ds_read_b128 v[202:205], v197 offset:57344
	v_add_f32_e32 v64, v159, v64
	v_add_f32_e32 v64, v144, v64
	v_add_f32_e32 v64, v145, v64
	v_add_f32_e32 v64, v146, v64
	v_add_u32_e32 v197, s4, v192
	v_add_f32_e32 v64, v147, v64
	s_waitcnt lgkmcnt(1)
	v_mfma_f32_32x32x16_bf16 v[96:111], v[198:201], v[120:123], v[96:111]
	ds_read_b128 v[198:201], v197 offset:49152
	ds_read_b128 v[206:209], v197 offset:57344
	v_add_f32_e32 v64, v148, v64
	v_exp_f32_e32 v222, v65
	v_add_f32_e32 v64, v149, v64
	v_exp_f32_e32 v223, v66
	v_add_f32_e32 v64, v150, v64
	v_exp_f32_e32 v224, v67
	s_waitcnt lgkmcnt(2)
	v_mfma_f32_32x32x16_bf16 v[80:95], v[202:205], v[120:123], v[80:95]
	v_add_f32_e32 v64, v151, v64
	v_add_f32_e32 v64, v221, v64
	v_add_f32_e32 v64, v222, v64
	v_add_f32_e32 v64, v223, v64
	v_exp_f32_e32 v71, v71
	v_add_f32_e32 v64, v224, v64
	v_add_u32_e32 v197, s4, v194
	s_waitcnt lgkmcnt(1)
	v_mfma_f32_32x32x16_bf16 v[96:111], v[198:201], v[116:119], v[96:111]
	v_exp_f32_e32 v199, v68
	v_exp_f32_e32 v200, v69
	v_exp_f32_e32 v201, v70
	v_exp_f32_e32 v225, v72
	v_add_f32_e32 v64, v199, v64
	ds_read_b128 v[202:205], v197 offset:49152
	ds_read_b128 v[210:213], v197 offset:57344
	v_exp_f32_e32 v226, v73
	s_waitcnt lgkmcnt(2)
	v_mfma_f32_32x32x16_bf16 v[80:95], v[206:209], v[116:119], v[80:95]
	v_add_f32_e32 v64, v200, v64
	v_exp_f32_e32 v227, v74
	v_add_f32_e32 v64, v201, v64
	v_exp_f32_e32 v206, v75
	v_add_f32_e32 v64, v71, v64
	v_exp_f32_e32 v207, v76
	v_add_f32_e32 v64, v225, v64
	v_exp_f32_e32 v208, v77
	v_add_f32_e32 v64, v226, v64
	v_exp_f32_e32 v209, v78
	s_waitcnt lgkmcnt(1)
	v_mfma_f32_32x32x16_bf16 v[96:111], v[202:205], v[112:115], v[96:111]
	v_add_f32_e32 v64, v227, v64
	v_exp_f32_e32 v79, v79
	v_add_f32_e32 v64, v206, v64
	v_add_f32_e32 v64, v207, v64
	v_add_f32_e32 v64, v208, v64
	v_add_f32_e32 v64, v209, v64
	v_add_f32_e32 v197, v79, v64
	s_waitcnt lgkmcnt(0)
	v_mfma_f32_32x32x16_bf16 v[80:95], v[210:213], v[112:115], v[80:95]
	v_mov_b32_e32 v198, v197
	v_cvt_pk_bf16_f32 v64, v152, v153
	v_cvt_pk_bf16_f32 v65, v154, v155
	v_cvt_pk_bf16_f32 v66, v156, v157
	v_cvt_pk_bf16_f32 v67, v158, v159
	v_cvt_pk_bf16_f32 v72, v144, v145
	v_cvt_pk_bf16_f32 v73, v146, v147
	v_cvt_pk_bf16_f32 v74, v148, v149
	v_cvt_pk_bf16_f32 v75, v150, v151
	v_cvt_pk_bf16_f32 v68, v221, v222
	v_cvt_pk_bf16_f32 v69, v223, v224
	v_cvt_pk_bf16_f32 v70, v199, v200
	v_cvt_pk_bf16_f32 v71, v201, v71
	v_cvt_pk_bf16_f32 v76, v225, v226
	v_cvt_pk_bf16_f32 v77, v227, v206
	v_cvt_pk_bf16_f32 v78, v207, v208
	v_cvt_pk_bf16_f32 v79, v209, v79
	v_permlane32_swap_b32_e32 v197, v198
	v_permlane32_swap_b32_e32 v64, v66
	v_permlane32_swap_b32_e32 v65, v67
	v_permlane32_swap_b32_e32 v72, v74
	v_permlane32_swap_b32_e32 v73, v75
	v_permlane32_swap_b32_e32 v68, v70
	v_permlane32_swap_b32_e32 v69, v71
	v_permlane32_swap_b32_e32 v76, v78
	v_permlane32_swap_b32_e32 v77, v79
	global_load_dwordx4 v[144:147], v244, s[98:99]
	global_load_dwordx4 v[148:151], v245, s[98:99]
	global_load_dwordx4 v[152:155], v242, s[98:99]
	global_load_dwordx4 v[156:159], v243, s[98:99]
	s_add_u32 s98, s98, 0x10000
	s_addc_u32 s99, s99, 0
	v_lshl_add_u32 v199, s18, 14, v181
	ds_read_b64_tr_b16 v[200:201], v199 offset:0
	ds_read_b64_tr_b16 v[202:203], v199 offset:0x800
	ds_read_b64_tr_b16 v[204:205], v199 offset:0x1000
	ds_read_b64_tr_b16 v[206:207], v199 offset:0x1800
	ds_read_b64_tr_b16 v[208:209], v199 offset:0x2000
	ds_read_b64_tr_b16 v[210:211], v199 offset:0x2800
	ds_read_b64_tr_b16 v[222:223], v199 offset:0x3000
	ds_read_b64_tr_b16 v[224:225], v199 offset:0x3800
	s_nop 0
	s_waitcnt lgkmcnt(6)
	v_mfma_f32_32x32x16_bf16 v[0:15], v[64:67], v[200:203], v[0:15]
	v_max_f32_e32 v200, v97, v97
	v_max_f32_e32 v201, v96, v96
	v_max_f32_e32 v200, v201, v200
	v_max3_f32 v200, v200, v98, v99
	v_max3_f32 v200, v200, v100, v101
	v_max3_f32 v200, v200, v102, v103
	v_max3_f32 v200, v200, v104, v105
	s_waitcnt lgkmcnt(4)
	v_mfma_f32_32x32x16_bf16 v[0:15], v[72:75], v[204:207], v[0:15]
	v_max3_f32 v200, v200, v106, v107
	v_max3_f32 v202, v200, v108, v109
	ds_read_b64_tr_b16 v[200:201], v199 offset:0x200
	v_max3_f32 v212, v202, v110, v111
	ds_read_b64_tr_b16 v[202:203], v199 offset:0xa00
	ds_read_b64_tr_b16 v[204:205], v199 offset:0x1200
	ds_read_b64_tr_b16 v[206:207], v199 offset:0x1a00
	s_waitcnt lgkmcnt(6)
	v_mfma_f32_32x32x16_bf16 v[0:15], v[68:71], v[208:211], v[0:15]
	ds_read_b64_tr_b16 v[208:209], v199 offset:0x2200
	ds_read_b64_tr_b16 v[210:211], v199 offset:0x2a00
	ds_read_b64_tr_b16 v[226:227], v199 offset:0x3200
	ds_read_b64_tr_b16 v[228:229], v199 offset:0x3a00
	s_waitcnt lgkmcnt(8)
	v_mfma_f32_32x32x16_bf16 v[0:15], v[76:79], v[222:225], v[0:15]
	s_waitcnt lgkmcnt(6)
	v_mfma_f32_32x32x16_bf16 v[48:63], v[64:67], v[200:203], v[48:63]
	v_max3_f32 v212, v212, v80, v81
	v_max3_f32 v200, v212, v82, v83
	ds_read_b64_tr_b16 v[202:203], v199 offset:0x400
	v_max3_f32 v200, v200, v84, v85
	v_max3_f32 v200, v200, v86, v87
	v_max3_f32 v200, v200, v88, v89
	v_max3_f32 v200, v200, v90, v91
	s_waitcnt lgkmcnt(5)
	v_mfma_f32_32x32x16_bf16 v[48:63], v[72:75], v[204:207], v[48:63]
	ds_read_b64_tr_b16 v[204:205], v199 offset:0xc00
	ds_read_b64_tr_b16 v[206:207], v199 offset:0x1400
	v_max3_f32 v200, v200, v92, v93
	v_max3_f32 v200, v200, v94, v95
	v_mov_b32_e32 v201, v200
	s_nop 1
	v_permlane32_swap_b32_e32 v200, v201
	s_waitcnt lgkmcnt(5)
	v_mfma_f32_32x32x16_bf16 v[48:63], v[68:71], v[208:211], v[48:63]
	ds_read_b64_tr_b16 v[208:209], v199 offset:0x1c00
	ds_read_b64_tr_b16 v[210:211], v199 offset:0x2400
	ds_read_b64_tr_b16 v[212:213], v199 offset:0x2c00
	ds_read_b64_tr_b16 v[222:223], v199 offset:0x3400
	ds_read_b64_tr_b16 v[224:225], v199 offset:0x3c00
	v_max_f32_e32 v201, v201, v201
	s_waitcnt lgkmcnt(8)
	v_mfma_f32_32x32x16_bf16 v[48:63], v[76:79], v[226:229], v[48:63]
	v_max_f32_e32 v200, v200, v200
	v_max_f32_e32 v200, v200, v201
	s_waitcnt lgkmcnt(6)
	v_mfma_f32_32x32x16_bf16 v[32:47], v[64:67], v[202:205], v[32:47]
	v_cmp_ge_f32_e32 vcc, s63, v200
	s_cmp_eq_u64 vcc, exec
	s_waitcnt lgkmcnt(4)
	v_mfma_f32_32x32x16_bf16 v[32:47], v[72:75], v[206:209], v[32:47]
	s_waitcnt lgkmcnt(2)
	v_mfma_f32_32x32x16_bf16 v[32:47], v[68:71], v[210:213], v[32:47]
	s_waitcnt lgkmcnt(0)
	v_mfma_f32_32x32x16_bf16 v[32:47], v[76:79], v[222:225], v[32:47]
	s_cbranch_scc0 .LBB0_438
	v_mov_b32_e32 v200, 1.0

.LBB0_431:
	v_add_u32_e32 v203, s16, v181
	ds_read_b64_tr_b16 v[204:205], v203 offset:0
	ds_read_b64_tr_b16 v[206:207], v203 offset:0x800
	ds_read_b64_tr_b16 v[208:209], v203 offset:0x1000
	ds_read_b64_tr_b16 v[210:211], v203 offset:0x1800
	ds_read_b64_tr_b16 v[222:223], v203 offset:0x2000
	ds_read_b64_tr_b16 v[224:225], v203 offset:0x2800
	ds_read_b64_tr_b16 v[226:227], v203 offset:0x3000
	ds_read_b64_tr_b16 v[228:229], v203 offset:0x3800
	s_waitcnt lgkmcnt(0)
	s_nop 0
	v_mfma_f32_32x32x16_bf16 v[0:15], v[88:91], v[204:207], v[0:15]
	v_max_f32_e32 v199, v97, v97
	v_max_f32_e32 v204, v96, v96
	v_max_f32_e32 v199, v204, v199
	ds_read_b64_tr_b16 v[204:205], v203 offset:0x200
	ds_read_b64_tr_b16 v[206:207], v203 offset:0xa00
	v_max3_f32 v199, v199, v98, v99
	v_max3_f32 v199, v199, v100, v101
	v_mfma_f32_32x32x16_bf16 v[0:15], v[92:95], v[208:211], v[0:15]
	ds_read_b64_tr_b16 v[208:209], v203 offset:0x1200
	ds_read_b64_tr_b16 v[210:211], v203 offset:0x1a00
	v_max3_f32 v199, v199, v102, v103
	v_max3_f32 v199, v199, v104, v105
	v_max3_f32 v199, v199, v106, v107
	v_max3_f32 v199, v199, v108, v109
	v_max3_f32 v199, v199, v110, v111
	v_mfma_f32_32x32x16_bf16 v[0:15], v[80:83], v[222:225], v[0:15]
	ds_read_b64_tr_b16 v[222:223], v203 offset:0x2200
	ds_read_b64_tr_b16 v[224:225], v203 offset:0x2a00
	ds_read_b64_tr_b16 v[230:231], v203 offset:0x3200
	ds_read_b64_tr_b16 v[232:233], v203 offset:0x3a00
	v_mfma_f32_32x32x16_bf16 v[0:15], v[84:87], v[226:229], v[0:15]
	s_waitcnt lgkmcnt(6)
	v_mfma_f32_32x32x16_bf16 v[48:63], v[88:91], v[204:207], v[48:63]
	v_max3_f32 v199, v199, v64, v65
	v_max3_f32 v199, v199, v66, v67
	ds_read_b64_tr_b16 v[206:207], v203 offset:0x400
	v_max3_f32 v199, v199, v68, v69
	v_max3_f32 v199, v199, v70, v71
	v_max3_f32 v199, v199, v72, v73
	v_max3_f32 v199, v199, v74, v75
	s_waitcnt lgkmcnt(5)
	v_mfma_f32_32x32x16_bf16 v[48:63], v[92:95], v[208:211], v[48:63]
	ds_read_b64_tr_b16 v[208:209], v203 offset:0xc00
	ds_read_b64_tr_b16 v[210:211], v203 offset:0x1400
	ds_read_b64_tr_b16 v[212:213], v203 offset:0x1c00
	v_max3_f32 v199, v199, v76, v77
	v_max3_f32 v199, v199, v78, v79
	v_mov_b32_e32 v204, v199
	s_nop 1
	v_permlane32_swap_b32_e32 v199, v204
	s_waitcnt lgkmcnt(6)
	v_mfma_f32_32x32x16_bf16 v[48:63], v[80:83], v[222:225], v[48:63]
	ds_read_b64_tr_b16 v[222:223], v203 offset:0x2400
	ds_read_b64_tr_b16 v[224:225], v203 offset:0x2c00
	ds_read_b64_tr_b16 v[226:227], v203 offset:0x3400
	ds_read_b64_tr_b16 v[228:229], v203 offset:0x3c00
	v_max_f32_e32 v204, v204, v204
	v_max_f32_e32 v199, v199, v199
	s_waitcnt lgkmcnt(8)
	v_mfma_f32_32x32x16_bf16 v[48:63], v[84:87], v[230:233], v[48:63]
	v_max_f32_e32 v204, v199, v204
	s_waitcnt lgkmcnt(6)
	v_mfma_f32_32x32x16_bf16 v[32:47], v[88:91], v[206:209], v[32:47]
	v_cmp_ge_f32_e32 vcc, s63, v204
	s_cmp_eq_u64 vcc, exec
	v_mov_b32_e32 v199, 1.0
	s_waitcnt lgkmcnt(4)
	v_mfma_f32_32x32x16_bf16 v[32:47], v[92:95], v[210:213], v[32:47]
	s_waitcnt lgkmcnt(2)
	v_mfma_f32_32x32x16_bf16 v[32:47], v[80:83], v[222:225], v[32:47]
	s_waitcnt lgkmcnt(0)
	v_mfma_f32_32x32x16_bf16 v[32:47], v[84:87], v[226:229], v[32:47]
	s_cbranch_scc0 .LBB0_439

.LBB0_619:
	v_and_b32_e32 v242, 7, v214
	v_bfe_u32 v243, v214, 3, 3
	v_lshrrev_b32_e32 v244, 6, v214
	v_lshlrev_b32_e32 v230, 16, v242
	v_lshl_or_b32 v230, v244, 7, v230
	v_lshl_or_b32 v230, v243, 4, v230
	v_add_u32_e32 v239, 0x80000, v230
	v_add_u32_e32 v240, 0x100000, v230
	v_add_u32_e32 v241, 0x180000, v230
	v_and_b32_e32 v245, 3, v242
	v_lshrrev_b32_e32 v246, 2, v242
	v_lshlrev_b32_e32 v247, 1, v243
	v_and_b32_e32 v247, 6, v247
	v_or_b32_e32 v246, v246, v247
	v_lshlrev_b32_e32 v244, 12, v244
	v_lshl_or_b32 v244, v243, 9, v244
	v_lshl_or_b32 v244, v245, 2, v244
	v_add_u32_e32 v244, 16, v244
	v_lshl_add_u32 v231, v246, 4, v244
	v_xor_b32_e32 v247, 1, v246
	v_lshl_add_u32 v232, v247, 4, v244
	v_xor_b32_e32 v247, 2, v246
	v_lshl_add_u32 v233, v247, 4, v244
	v_xor_b32_e32 v247, 3, v246
	v_lshl_add_u32 v234, v247, 4, v244
	v_xor_b32_e32 v247, 4, v246
	v_lshl_add_u32 v235, v247, 4, v244
	v_xor_b32_e32 v247, 5, v246
	v_lshl_add_u32 v236, v247, 4, v244
	v_xor_b32_e32 v247, 6, v246
	v_lshl_add_u32 v237, v247, 4, v244
	v_xor_b32_e32 v247, 7, v246
	v_lshl_add_u32 v238, v247, 4, v244
	s_lshl_b32 s0, s2, 8
	s_and_b32 s19, s0, 0x3f00
	s_lshl_b32 s0, s2, 2
	s_and_b32 s21, s9, 0xffffff00
	s_and_b32 s20, s0, 0xffffff00
	s_lshl_b32 s22, s19, 9
	s_lshl_b32 s0, s19, 10
	v_mov_b32_e32 v35, v221
	s_add_u32 s0, s7, s0
	s_addc_u32 s1, s8, 0
	v_ashrrev_i32_e32 v32, 3, v35
	s_mul_i32 s4, s20, 0xc00
	v_lshlrev_b32_e32 v0, 3, v35
	s_mul_hi_i32 s5, s20, 0xc00
	s_add_u32 s4, s3, s4
	v_and_b32_e32 v34, 56, v0
	v_add_u32_e32 v8, 64, v32
	v_add_u32_e32 v22, 0x80, v32
	v_add_u32_e32 v30, 0xc0, v32
	s_addc_u32 s5, s6, s5
	v_lshlrev_b32_e32 v208, 1, v34
	v_ashrrev_i32_e32 v33, 31, v32
	v_ashrrev_i32_e32 v9, 31, v8
	v_ashrrev_i32_e32 v23, 31, v22
	v_ashrrev_i32_e32 v31, 31, v30
	v_lshl_add_u64 v[20:21], s[0:1], 0, v[208:209]
	v_lshl_add_u64 v[28:29], s[4:5], 0, v[208:209]
	v_lshlrev_b64 v[128:129], 10, v[32:33]
	v_lshlrev_b64 v[130:131], 10, v[8:9]
	v_lshlrev_b64 v[132:133], 10, v[22:23]
	v_lshlrev_b64 v[134:135], 10, v[30:31]
	v_lshl_add_u64 v[0:1], v[20:21], 0, v[128:129]
	v_mad_i64_i32 v[4:5], s[0:1], v32, s11, v[28:29]
	v_lshl_add_u64 v[10:11], v[20:21], 0, v[130:131]
	v_mad_i64_i32 v[12:13], s[0:1], v8, s11, v[28:29]
	v_lshl_add_u64 v[16:17], v[20:21], 0, v[132:133]
	v_mad_i64_i32 v[24:25], s[0:1], v22, s11, v[28:29]
	v_lshl_add_u64 v[20:21], v[20:21], 0, v[134:135]
	s_barrier
	global_load_dwordx4 v[0:3], v[0:1], off
	s_nop 0
	global_load_dwordx4 v[4:7], v[4:5], off
	s_nop 0
	global_load_dwordx4 v[8:11], v[10:11], off
	s_nop 0
	global_load_dwordx4 v[12:15], v[12:13], off
	v_mad_i64_i32 v[28:29], s[0:1], v30, s11, v[28:29]
	global_load_dwordx4 v[16:19], v[16:17], off
	s_nop 0
	global_load_dwordx4 v[20:23], v[20:21], off
	s_nop 0
	global_load_dwordx4 v[24:27], v[24:25], off
	v_lshrrev_b32_e32 v33, 5, v35
	global_load_dwordx4 v[28:31], v[28:29], off
	v_bfe_u32 v38, v35, 1, 3
	v_lshrrev_b32_e32 v40, 1, v32
	v_bitop3_b32 v33, v33, v38, 1 bitop3:0x6c
	v_xor_b32_e32 v40, v40, v35
	v_lshlrev_b32_e32 v39, 7, v32
	v_lshlrev_b32_e32 v139, 4, v33
	v_lshlrev_b32_e32 v33, 4, v40
	v_and_or_b32 v33, v33, s12, v39
	s_mul_hi_i32 s0, s21, 0xc00
	s_mulk_i32 s21, 0xc00
	v_bfe_u32 v212, v35, 5, 1
	v_add_u32_e32 v140, 16, v33
	v_mov_b32_e32 v36, s21
	v_mov_b32_e32 v37, s0
	v_ashrrev_i32_e32 v211, 8, v35
	v_and_b32_e32 v210, 31, v35
	v_bfe_u32 v213, v35, 6, 2
	v_bitop3_b32 v41, v212, v38, 2 bitop3:0x36
	v_bitop3_b32 v42, v212, v38, 4 bitop3:0x36
	v_lshlrev_b32_e32 v166, 14, v211
	v_lshlrev_b32_e32 v164, 7, v210
	v_lshlrev_b32_e32 v165, 13, v213
	v_lshlrev_b32_e32 v138, 4, v41
	v_lshlrev_b32_e32 v144, 4, v42
	s_lshl_b32 s21, s22, 1
	v_lshlrev_b32_e32 v208, 1, v34
	s_mov_b32 s22, 64
	s_mov_b32 s23, 0
	s_mov_b32 s4, 0
	v_mov_b32_e32 v33, v209
	v_mov_b32_e32 v34, v209
	v_mov_b32_e32 v39, v209
	v_mov_b32_e32 v40, v209
	v_mov_b32_e32 v41, v209
	v_mov_b32_e32 v42, v209
	v_mov_b32_e32 v43, v209
	s_waitcnt vmcnt(7)
	ds_write_b128 v140, v[0:3]
	s_waitcnt vmcnt(5)
	ds_write_b128 v140, v[8:11] offset:8192
	s_waitcnt vmcnt(3)
	ds_write_b128 v140, v[16:19] offset:16384
	s_waitcnt vmcnt(2)
	ds_write_b128 v140, v[20:23] offset:24576
	ds_write_b128 v140, v[4:7] offset:32768
	ds_write_b128 v140, v[12:15] offset:40960
	s_waitcnt vmcnt(1)
	ds_write_b128 v140, v[24:27] offset:49152
	s_waitcnt vmcnt(0)
	ds_write_b128 v140, v[28:31] offset:57344
	v_bitop3_b32 v0, v212, v38, 6 bitop3:0x36
	v_lshlrev_b32_e32 v167, 4, v0
	v_mad_i64_i32 v[0:1], s[0:1], v32, s11, v[36:37]
	v_and_b32_e32 v2, 7, v35
	v_lshl_or_b32 v0, v2, 4, v0
	v_lshl_add_u64 v[136:137], s[86:87], 0, v[0:1]
	s_mov_b64 s[0:1], 0
	v_mov_b32_e32 v0, v209
	v_mov_b32_e32 v1, v209
	v_mov_b32_e32 v2, v209
	v_mov_b32_e32 v3, v209
	v_mov_b32_e32 v4, v209
	v_mov_b32_e32 v5, v209
	v_mov_b32_e32 v6, v209
	v_mov_b32_e32 v7, v209
	v_mov_b32_e32 v8, v209
	v_mov_b32_e32 v9, v209
	v_mov_b32_e32 v10, v209
	v_mov_b32_e32 v11, v209
	v_mov_b32_e32 v12, v209
	v_mov_b32_e32 v13, v209
	v_mov_b32_e32 v14, v209
	v_mov_b32_e32 v15, v209
	v_mov_b32_e32 v16, v209
	v_mov_b32_e32 v17, v209
	v_mov_b32_e32 v18, v209
	v_mov_b32_e32 v19, v209
	v_mov_b32_e32 v20, v209
	v_mov_b32_e32 v21, v209
	v_mov_b32_e32 v22, v209
	v_mov_b32_e32 v23, v209
	v_mov_b32_e32 v24, v209
	v_mov_b32_e32 v25, v209
	v_mov_b32_e32 v26, v209
	v_mov_b32_e32 v27, v209
	v_mov_b32_e32 v28, v209
	v_mov_b32_e32 v29, v209
	v_mov_b32_e32 v30, v209
	v_mov_b32_e32 v31, v209
	v_mov_b32_e32 v32, v209
	v_mov_b32_e32 v35, v209
	v_mov_b32_e32 v36, v209
	v_mov_b32_e32 v37, v209
	v_mov_b32_e32 v38, v209
	v_mov_b32_e32 v44, v209
	v_mov_b32_e32 v45, v209
	v_mov_b32_e32 v46, v209
	v_mov_b32_e32 v47, v209
	v_mov_b32_e32 v48, v209
	v_mov_b32_e32 v49, v209
	v_mov_b32_e32 v50, v209
	v_mov_b32_e32 v51, v209
	v_mov_b32_e32 v52, v209
	v_mov_b32_e32 v53, v209
	v_mov_b32_e32 v54, v209
	v_mov_b32_e32 v55, v209
	v_mov_b32_e32 v56, v209
	v_mov_b32_e32 v57, v209
	v_mov_b32_e32 v58, v209
	v_mov_b32_e32 v59, v209
	v_mov_b32_e32 v60, v209
	v_mov_b32_e32 v61, v209
	v_mov_b32_e32 v62, v209
	v_mov_b32_e32 v63, v209
	v_mov_b32_e32 v64, v209
	v_mov_b32_e32 v65, v209
	v_mov_b32_e32 v66, v209
	v_mov_b32_e32 v67, v209
	v_mov_b32_e32 v68, v209
	v_mov_b32_e32 v69, v209
	v_mov_b32_e32 v70, v209
	v_mov_b32_e32 v71, v209
	v_mov_b32_e32 v72, v209
	v_mov_b32_e32 v73, v209
	v_mov_b32_e32 v74, v209
	v_mov_b32_e32 v75, v209
	v_mov_b32_e32 v76, v209
	v_mov_b32_e32 v77, v209
	v_mov_b32_e32 v78, v209
	v_mov_b32_e32 v79, v209
	v_mov_b32_e32 v80, v209
	v_mov_b32_e32 v81, v209
	v_mov_b32_e32 v82, v209
	v_mov_b32_e32 v83, v209
	v_mov_b32_e32 v84, v209
	v_mov_b32_e32 v85, v209
	v_mov_b32_e32 v86, v209
	v_mov_b32_e32 v87, v209
	v_mov_b32_e32 v88, v209
	v_mov_b32_e32 v89, v209
	v_mov_b32_e32 v90, v209
	v_mov_b32_e32 v91, v209
	v_mov_b32_e32 v92, v209
	v_mov_b32_e32 v93, v209
	v_mov_b32_e32 v94, v209
	v_mov_b32_e32 v95, v209
	v_mov_b32_e32 v96, v209
	v_mov_b32_e32 v97, v209
	v_mov_b32_e32 v98, v209
	v_mov_b32_e32 v99, v209
	v_mov_b32_e32 v100, v209
	v_mov_b32_e32 v101, v209
	v_mov_b32_e32 v102, v209
	v_mov_b32_e32 v103, v209
	v_mov_b32_e32 v104, v209
	v_mov_b32_e32 v105, v209
	v_mov_b32_e32 v106, v209
	v_mov_b32_e32 v107, v209
	v_mov_b32_e32 v108, v209
	v_mov_b32_e32 v109, v209
	v_mov_b32_e32 v110, v209
	v_mov_b32_e32 v111, v209
	v_mov_b32_e32 v112, v209
	v_mov_b32_e32 v113, v209
	v_mov_b32_e32 v114, v209
	v_mov_b32_e32 v115, v209
	v_mov_b32_e32 v116, v209
	v_mov_b32_e32 v117, v209
	v_mov_b32_e32 v118, v209
	v_mov_b32_e32 v119, v209
	v_mov_b32_e32 v120, v209
	v_mov_b32_e32 v121, v209
	v_mov_b32_e32 v122, v209
	v_mov_b32_e32 v123, v209
	v_mov_b32_e32 v124, v209
	v_mov_b32_e32 v125, v209
	v_mov_b32_e32 v126, v209
	v_mov_b32_e32 v127, v209
	s_waitcnt lgkmcnt(0)
	s_barrier

.Lyb_ld_L0:
	global_load_dwordx4 v[184:187], v230, s[98:99]
	global_load_dwordx4 v[188:191], v239, s[98:99]
	global_load_dwordx4 v[192:195], v240, s[98:99]
	s_waitcnt lgkmcnt(1)
	v_mfma_f32_32x32x16_bf16 v[48:63], v[154:157], v[150:153], v[48:63]
	v_mfma_f32_32x32x16_bf16 v[32:47], v[154:157], v[158:161], v[32:47]
	global_load_dwordx4 v[154:157], v241, s[98:99]

.Lyb_wr_L0:
	v_add_u32_e32 v242, s5, v231
	v_add_u32_e32 v243, s5, v232
	v_add_u32_e32 v244, s5, v233
	v_add_u32_e32 v245, s5, v234
	v_add_u32_e32 v246, s5, v235
	v_add_u32_e32 v247, s5, v236
	v_add_u32_e32 v248, s5, v237
	v_add_u32_e32 v249, s5, v238
	s_waitcnt vmcnt(3)
	ds_write_b32 v242, v184
	ds_write_b32 v242, v185 offset:128
	ds_write_b32 v243, v186 offset:256
	ds_write_b32 v243, v187 offset:384
	s_waitcnt vmcnt(2)
	ds_write_b32 v244, v188
	ds_write_b32 v244, v189 offset:128
	ds_write_b32 v245, v190 offset:256
	ds_write_b32 v245, v191 offset:384
	s_waitcnt vmcnt(1)
	ds_write_b32 v246, v192
	ds_write_b32 v246, v193 offset:128
	ds_write_b32 v247, v194 offset:256
	ds_write_b32 v247, v195 offset:384
	s_waitcnt vmcnt(0)
	ds_write_b32 v248, v154
	ds_write_b32 v248, v155 offset:128
	ds_write_b32 v249, v156 offset:256
	ds_write_b32 v249, v157 offset:384

.LBB0_991:
	v_and_b32_e32 v242, 7, v214
	v_bfe_u32 v243, v214, 3, 3
	v_lshrrev_b32_e32 v244, 6, v214
	v_lshlrev_b32_e32 v230, 16, v242
	v_lshl_or_b32 v230, v244, 7, v230
	v_lshl_or_b32 v230, v243, 4, v230
	v_add_u32_e32 v239, 0x80000, v230
	v_add_u32_e32 v240, 0x100000, v230
	v_add_u32_e32 v241, 0x180000, v230
	v_and_b32_e32 v245, 3, v242
	v_lshrrev_b32_e32 v246, 2, v242
	v_lshlrev_b32_e32 v247, 1, v243
	v_and_b32_e32 v247, 6, v247
	v_or_b32_e32 v246, v246, v247
	v_lshlrev_b32_e32 v244, 12, v244
	v_lshl_or_b32 v244, v243, 9, v244
	v_lshl_or_b32 v244, v245, 2, v244
	v_add_u32_e32 v244, 16, v244
	v_lshl_add_u32 v231, v246, 4, v244
	v_xor_b32_e32 v247, 1, v246
	v_lshl_add_u32 v232, v247, 4, v244
	v_xor_b32_e32 v247, 2, v246
	v_lshl_add_u32 v233, v247, 4, v244
	v_xor_b32_e32 v247, 3, v246
	v_lshl_add_u32 v234, v247, 4, v244
	v_xor_b32_e32 v247, 4, v246
	v_lshl_add_u32 v235, v247, 4, v244
	v_xor_b32_e32 v247, 5, v246
	v_lshl_add_u32 v236, v247, 4, v244
	v_xor_b32_e32 v247, 6, v246
	v_lshl_add_u32 v237, v247, 4, v244
	v_xor_b32_e32 v247, 7, v246
	v_lshl_add_u32 v238, v247, 4, v244
	s_lshl_b32 s0, s2, 8
	s_and_b32 s19, s0, 0x3f00
	s_lshl_b32 s0, s2, 2
	s_and_b32 s21, s9, 0xffffff00
	s_and_b32 s20, s0, 0xffffff00
	v_mov_b32_e32 v35, v176
	s_lshl_b32 s22, s19, 9
	s_lshl_b32 s0, s19, 10
	s_add_u32 s0, s7, s0
	v_lshlrev_b32_e32 v0, 3, v35
	v_ashrrev_i32_e32 v32, 3, v35
	s_addc_u32 s1, s8, 0
	s_mul_i32 s4, s20, 0xc00
	v_and_b32_e32 v34, 56, v0
	s_mul_hi_i32 s5, s20, 0xc00
	s_add_u32 s4, s3, s4
	v_lshlrev_b32_e32 v164, 1, v34
	v_ashrrev_i32_e32 v33, 31, v32
	s_addc_u32 s5, s6, s5
	v_lshl_add_u64 v[20:21], s[0:1], 0, v[164:165]
	v_lshlrev_b64 v[128:129], 10, v[32:33]
	v_lshl_add_u64 v[28:29], s[4:5], 0, v[164:165]
	v_lshl_add_u64 v[8:9], v[20:21], 0, v[128:129]
	s_barrier
	v_mad_i64_i32 v[10:11], s[0:1], v32, s11, v[28:29]
	global_load_dwordx4 v[0:3], v[8:9], off
	global_load_dwordx4 v[4:7], v[10:11], off
	v_add_u32_e32 v8, 64, v32
	v_ashrrev_i32_e32 v9, 31, v8
	v_add_u32_e32 v22, 0x80, v32
	v_add_u32_e32 v36, 0xc0, v32
	v_lshlrev_b64 v[130:131], 10, v[8:9]
	v_ashrrev_i32_e32 v23, 31, v22
	v_ashrrev_i32_e32 v37, 31, v36
	v_lshl_add_u64 v[16:17], v[20:21], 0, v[130:131]
	v_lshlrev_b64 v[132:133], 10, v[22:23]
	v_lshlrev_b64 v[134:135], 10, v[36:37]
	v_mad_i64_i32 v[18:19], s[0:1], v8, s11, v[28:29]
	global_load_dwordx4 v[8:11], v[16:17], off
	global_load_dwordx4 v[12:15], v[18:19], off
	v_lshl_add_u64 v[16:17], v[20:21], 0, v[132:133]
	v_lshl_add_u64 v[38:39], v[20:21], 0, v[134:135]
	global_load_dwordx4 v[16:19], v[16:17], off
	v_mad_i64_i32 v[30:31], s[0:1], v22, s11, v[28:29]
	global_load_dwordx4 v[20:23], v[38:39], off
	global_load_dwordx4 v[24:27], v[30:31], off
	v_mad_i64_i32 v[28:29], s[0:1], v36, s11, v[28:29]
	global_load_dwordx4 v[28:31], v[28:29], off
	v_lshrrev_b32_e32 v33, 5, v35
	v_bfe_u32 v38, v35, 1, 3
	v_lshrrev_b32_e32 v40, 1, v32
	v_bitop3_b32 v33, v33, v38, 1 bitop3:0x6c
	v_xor_b32_e32 v40, v40, v35
	v_lshlrev_b32_e32 v39, 7, v32
	v_lshlrev_b32_e32 v143, 4, v33
	v_lshlrev_b32_e32 v33, 4, v40
	v_and_or_b32 v33, v33, s12, v39
	s_mul_hi_i32 s0, s21, 0xc00
	s_mulk_i32 s21, 0xc00
	v_bfe_u32 v168, v35, 5, 1
	v_add_u32_e32 v144, 16, v33
	v_mov_b32_e32 v36, s21
	v_mov_b32_e32 v37, s0
	v_ashrrev_i32_e32 v166, 8, v35
	v_and_b32_e32 v167, 31, v35
	v_bfe_u32 v169, v35, 6, 2
	v_bitop3_b32 v41, v168, v38, 2 bitop3:0x36
	v_bitop3_b32 v42, v168, v38, 4 bitop3:0x36
	v_lshlrev_b32_e32 v140, 14, v166
	v_lshlrev_b32_e32 v138, 7, v167
	v_lshlrev_b32_e32 v139, 13, v169
	v_lshlrev_b32_e32 v142, 4, v41
	v_lshlrev_b32_e32 v141, 4, v42
	s_lshl_b32 s21, s22, 1
	v_lshlrev_b32_e32 v164, 1, v34
	s_mov_b32 s22, 64
	s_mov_b32 s23, 0
	s_mov_b32 s4, 0
	v_mov_b32_e32 v33, v165
	v_mov_b32_e32 v34, v165
	v_mov_b32_e32 v39, v165
	v_mov_b32_e32 v40, v165
	v_mov_b32_e32 v41, v165
	v_mov_b32_e32 v42, v165
	v_mov_b32_e32 v43, v165
	v_mov_b32_e32 v44, v165
	v_mov_b32_e32 v45, v165
	v_mov_b32_e32 v46, v165
	v_mov_b32_e32 v47, v165
	s_waitcnt vmcnt(7)
	ds_write_b128 v144, v[0:3]
	s_waitcnt vmcnt(5)
	ds_write_b128 v144, v[8:11] offset:8192
	s_waitcnt vmcnt(3)
	ds_write_b128 v144, v[16:19] offset:16384
	s_waitcnt vmcnt(2)
	ds_write_b128 v144, v[20:23] offset:24576
	ds_write_b128 v144, v[4:7] offset:32768
	ds_write_b128 v144, v[12:15] offset:40960
	s_waitcnt vmcnt(1)
	ds_write_b128 v144, v[24:27] offset:49152
	s_waitcnt vmcnt(0)
	ds_write_b128 v144, v[28:31] offset:57344
	v_bitop3_b32 v0, v168, v38, 6 bitop3:0x36
	v_lshlrev_b32_e32 v170, 4, v0
	v_mad_i64_i32 v[0:1], s[0:1], v32, s11, v[36:37]
	v_and_b32_e32 v2, 7, v35
	v_lshl_or_b32 v0, v2, 4, v0
	v_lshl_add_u64 v[136:137], s[86:87], 0, v[0:1]
	s_mov_b64 s[0:1], 0
	v_mov_b32_e32 v0, v165
	v_mov_b32_e32 v1, v165
	v_mov_b32_e32 v2, v165
	v_mov_b32_e32 v3, v165
	v_mov_b32_e32 v4, v165
	v_mov_b32_e32 v5, v165
	v_mov_b32_e32 v6, v165
	v_mov_b32_e32 v7, v165
	v_mov_b32_e32 v8, v165
	v_mov_b32_e32 v9, v165
	v_mov_b32_e32 v10, v165
	v_mov_b32_e32 v11, v165
	v_mov_b32_e32 v12, v165
	v_mov_b32_e32 v13, v165
	v_mov_b32_e32 v14, v165
	v_mov_b32_e32 v15, v165
	v_mov_b32_e32 v16, v165
	v_mov_b32_e32 v17, v165
	v_mov_b32_e32 v18, v165
	v_mov_b32_e32 v19, v165
	v_mov_b32_e32 v20, v165
	v_mov_b32_e32 v21, v165
	v_mov_b32_e32 v22, v165
	v_mov_b32_e32 v23, v165
	v_mov_b32_e32 v24, v165
	v_mov_b32_e32 v25, v165
	v_mov_b32_e32 v26, v165
	v_mov_b32_e32 v27, v165
	v_mov_b32_e32 v28, v165
	v_mov_b32_e32 v29, v165
	v_mov_b32_e32 v30, v165
	v_mov_b32_e32 v31, v165
	v_mov_b32_e32 v32, v165
	v_mov_b32_e32 v35, v165
	v_mov_b32_e32 v36, v165
	v_mov_b32_e32 v37, v165
	v_mov_b32_e32 v38, v165
	v_mov_b32_e32 v48, v165
	v_mov_b32_e32 v49, v165
	v_mov_b32_e32 v50, v165
	v_mov_b32_e32 v51, v165
	v_mov_b32_e32 v52, v165
	v_mov_b32_e32 v53, v165
	v_mov_b32_e32 v54, v165
	v_mov_b32_e32 v55, v165
	v_mov_b32_e32 v56, v165
	v_mov_b32_e32 v57, v165
	v_mov_b32_e32 v58, v165
	v_mov_b32_e32 v59, v165
	v_mov_b32_e32 v60, v165
	v_mov_b32_e32 v61, v165
	v_mov_b32_e32 v62, v165
	v_mov_b32_e32 v63, v165
	v_mov_b32_e32 v64, v165
	v_mov_b32_e32 v65, v165
	v_mov_b32_e32 v66, v165
	v_mov_b32_e32 v67, v165
	v_mov_b32_e32 v68, v165
	v_mov_b32_e32 v69, v165
	v_mov_b32_e32 v70, v165
	v_mov_b32_e32 v71, v165
	v_mov_b32_e32 v72, v165
	v_mov_b32_e32 v73, v165
	v_mov_b32_e32 v74, v165
	v_mov_b32_e32 v75, v165
	v_mov_b32_e32 v76, v165
	v_mov_b32_e32 v77, v165
	v_mov_b32_e32 v78, v165
	v_mov_b32_e32 v79, v165
	v_mov_b32_e32 v80, v165
	v_mov_b32_e32 v81, v165
	v_mov_b32_e32 v82, v165
	v_mov_b32_e32 v83, v165
	v_mov_b32_e32 v84, v165
	v_mov_b32_e32 v85, v165
	v_mov_b32_e32 v86, v165
	v_mov_b32_e32 v87, v165
	v_mov_b32_e32 v88, v165
	v_mov_b32_e32 v89, v165
	v_mov_b32_e32 v90, v165
	v_mov_b32_e32 v91, v165
	v_mov_b32_e32 v92, v165
	v_mov_b32_e32 v93, v165
	v_mov_b32_e32 v94, v165
	v_mov_b32_e32 v95, v165
	v_mov_b32_e32 v96, v165
	v_mov_b32_e32 v97, v165
	v_mov_b32_e32 v98, v165
	v_mov_b32_e32 v99, v165
	v_mov_b32_e32 v100, v165
	v_mov_b32_e32 v101, v165
	v_mov_b32_e32 v102, v165
	v_mov_b32_e32 v103, v165
	v_mov_b32_e32 v104, v165
	v_mov_b32_e32 v105, v165
	v_mov_b32_e32 v106, v165
	v_mov_b32_e32 v107, v165
	v_mov_b32_e32 v108, v165
	v_mov_b32_e32 v109, v165
	v_mov_b32_e32 v110, v165
	v_mov_b32_e32 v111, v165
	v_mov_b32_e32 v112, v165
	v_mov_b32_e32 v113, v165
	v_mov_b32_e32 v114, v165
	v_mov_b32_e32 v115, v165
	v_mov_b32_e32 v116, v165
	v_mov_b32_e32 v117, v165
	v_mov_b32_e32 v118, v165
	v_mov_b32_e32 v119, v165
	v_mov_b32_e32 v120, v165
	v_mov_b32_e32 v121, v165
	v_mov_b32_e32 v122, v165
	v_mov_b32_e32 v123, v165
	v_mov_b32_e32 v124, v165
	v_mov_b32_e32 v125, v165
	v_mov_b32_e32 v126, v165
	v_mov_b32_e32 v127, v165
	s_waitcnt lgkmcnt(0)
	s_barrier

.Lyb_ld_L1:
	global_load_dwordx4 v[190:193], v230, s[98:99]
	global_load_dwordx4 v[194:197], v239, s[98:99]
	global_load_dwordx4 v[198:201], v240, s[98:99]
	s_waitcnt lgkmcnt(1)
	v_mfma_f32_32x32x16_bf16 v[48:63], v[154:157], v[150:153], v[48:63]
	v_mfma_f32_32x32x16_bf16 v[32:47], v[154:157], v[158:161], v[32:47]
	global_load_dwordx4 v[154:157], v241, s[98:99]

.Lyb_wr_L1:
	v_add_u32_e32 v242, s5, v231
	v_add_u32_e32 v243, s5, v232
	v_add_u32_e32 v244, s5, v233
	v_add_u32_e32 v245, s5, v234
	v_add_u32_e32 v246, s5, v235
	v_add_u32_e32 v247, s5, v236
	v_add_u32_e32 v248, s5, v237
	v_add_u32_e32 v249, s5, v238
	s_waitcnt vmcnt(3)
	ds_write_b32 v242, v190
	ds_write_b32 v242, v191 offset:128
	ds_write_b32 v243, v192 offset:256
	ds_write_b32 v243, v193 offset:384
	s_waitcnt vmcnt(2)
	ds_write_b32 v244, v194
	ds_write_b32 v244, v195 offset:128
	ds_write_b32 v245, v196 offset:256
	ds_write_b32 v245, v197 offset:384
	s_waitcnt vmcnt(1)
	ds_write_b32 v246, v198
	ds_write_b32 v246, v199 offset:128
	ds_write_b32 v247, v200 offset:256
	ds_write_b32 v247, v201 offset:384
	s_waitcnt vmcnt(0)
	ds_write_b32 v248, v154
	ds_write_b32 v248, v155 offset:128
	ds_write_b32 v249, v156 offset:256
	ds_write_b32 v249, v157 offset:384
